# thr histogram step: groups of four keys with no prefix match skip the bin/add work
# baseline (speedup 1.0000x reference)
; DI unsigned fkey(float s) {
;   const unsigned u = __float_as_uint(s);
;   return u ^ ((unsigned)((int)u >> 31) | 0x80000000u);
; }
; DI void dsa_thr_item(const Params& p, int b, int qblk, char* smem) {
;     ...
; #pragma unroll
;         for (int i = 0; i < 16; ++i) {
;           unsigned ky = fkey(sc[i]);
;           unsigned hi = (ky >> shift);
;           if ((hi >> 8) == mypref) atomicAdd(&hist[(hi & 255u) * 32 + lr], 1u);
;         }
.Lthr_h_gen:
	s_add_i32 s62, s58, 8
	v_lshrrev_b32_e32 v120, 8, v9
	v_and_b32_e32 v104, 0xff, v9
	v_ashrrev_i32_e32 v105, 31, v22
	v_ashrrev_i32_e32 v106, 31, v21
	v_ashrrev_i32_e32 v107, 31, v20
	v_bitop3_b32 v105, v105, v22, s67 bitop3:0x36
	v_bitop3_b32 v106, v106, v21, s67 bitop3:0x36
	v_bitop3_b32 v107, v107, v20, s67 bitop3:0x36
	v_lshrrev_b32_e32 v121, s62, v105
	v_lshrrev_b32_e32 v122, s62, v106
	v_lshrrev_b32_e32 v123, s62, v107
	v_cmp_eq_u32_e64 s[0:1], v120, v94
	v_cmp_eq_u32_e64 s[6:7], v121, v94
	v_cmp_eq_u32_e64 s[8:9], v122, v94
	v_cmp_eq_u32_e64 s[10:11], v123, v94
	s_or_b64 s[76:77], s[0:1], s[6:7]
	s_or_b64 s[84:85], s[8:9], s[10:11]
	s_or_b64 s[76:77], s[76:77], s[84:85]
	s_cbranch_scc0 .Lthr_g0_skip
	v_bfe_u32 v105, v105, s58, 8
	v_bfe_u32 v106, v106, s58, 8
	v_bfe_u32 v107, v107, s58, 8
	v_lshl_add_u32 v136, v104, 7, v58
	v_lshl_add_u32 v137, v105, 7, v58
	v_lshl_add_u32 v138, v106, 7, v58
	v_lshl_add_u32 v139, v107, 7, v58
	s_and_saveexec_b64 s[74:75], s[0:1]
	ds_add_u32 v136, v71
	s_mov_b64 exec, s[74:75]
	s_and_saveexec_b64 s[74:75], s[6:7]
	ds_add_u32 v137, v71
	s_mov_b64 exec, s[74:75]
	s_and_saveexec_b64 s[74:75], s[8:9]
	ds_add_u32 v138, v71
	s_mov_b64 exec, s[74:75]
	s_and_saveexec_b64 s[74:75], s[10:11]
	ds_add_u32 v139, v71
	s_mov_b64 exec, s[74:75]
.Lthr_g0_skip:
	v_ashrrev_i32_e32 v108, 31, v19
	v_ashrrev_i32_e32 v109, 31, v18
	v_ashrrev_i32_e32 v110, 31, v17
	v_ashrrev_i32_e32 v111, 31, v16
	v_bitop3_b32 v108, v108, v19, s67 bitop3:0x36
	v_bitop3_b32 v109, v109, v18, s67 bitop3:0x36
	v_bitop3_b32 v110, v110, v17, s67 bitop3:0x36
	v_bitop3_b32 v111, v111, v16, s67 bitop3:0x36
	v_lshrrev_b32_e32 v124, s62, v108
	v_lshrrev_b32_e32 v125, s62, v109
	v_lshrrev_b32_e32 v126, s62, v110
	v_lshrrev_b32_e32 v127, s62, v111
	v_cmp_eq_u32_e64 s[0:1], v124, v94
	v_cmp_eq_u32_e64 s[6:7], v125, v94
	v_cmp_eq_u32_e64 s[8:9], v126, v94
	v_cmp_eq_u32_e64 s[10:11], v127, v94
	s_or_b64 s[76:77], s[0:1], s[6:7]
	s_or_b64 s[84:85], s[8:9], s[10:11]
	s_or_b64 s[76:77], s[76:77], s[84:85]
	s_cbranch_scc0 .Lthr_g1_skip
	v_bfe_u32 v108, v108, s58, 8
	v_bfe_u32 v109, v109, s58, 8
	v_bfe_u32 v110, v110, s58, 8
	v_bfe_u32 v111, v111, s58, 8
	v_lshl_add_u32 v140, v108, 7, v58
	v_lshl_add_u32 v141, v109, 7, v58
	v_lshl_add_u32 v142, v110, 7, v58
	v_lshl_add_u32 v143, v111, 7, v58
	s_and_saveexec_b64 s[74:75], s[0:1]
	ds_add_u32 v140, v71
	s_mov_b64 exec, s[74:75]
	s_and_saveexec_b64 s[74:75], s[6:7]
	ds_add_u32 v141, v71
	s_mov_b64 exec, s[74:75]
	s_and_saveexec_b64 s[74:75], s[8:9]
	ds_add_u32 v142, v71
	s_mov_b64 exec, s[74:75]
	s_and_saveexec_b64 s[74:75], s[10:11]
	ds_add_u32 v143, v71
	s_mov_b64 exec, s[74:75]
.Lthr_g1_skip:
	v_ashrrev_i32_e32 v112, 31, v7
	v_ashrrev_i32_e32 v113, 31, v6
	v_ashrrev_i32_e32 v114, 31, v5
	v_ashrrev_i32_e32 v115, 31, v4
	v_bitop3_b32 v112, v112, v7, s67 bitop3:0x36
	v_bitop3_b32 v113, v113, v6, s67 bitop3:0x36
	v_bitop3_b32 v114, v114, v5, s67 bitop3:0x36
	v_bitop3_b32 v115, v115, v4, s67 bitop3:0x36
	v_lshrrev_b32_e32 v128, s62, v112
	v_lshrrev_b32_e32 v129, s62, v113
	v_lshrrev_b32_e32 v130, s62, v114
	v_lshrrev_b32_e32 v131, s62, v115
	v_cmp_eq_u32_e64 s[0:1], v128, v94
	v_cmp_eq_u32_e64 s[6:7], v129, v94
	v_cmp_eq_u32_e64 s[8:9], v130, v94
	v_cmp_eq_u32_e64 s[10:11], v131, v94
	s_or_b64 s[76:77], s[0:1], s[6:7]
	s_or_b64 s[84:85], s[8:9], s[10:11]
	s_or_b64 s[76:77], s[76:77], s[84:85]
	s_cbranch_scc0 .Lthr_g2_skip
	v_bfe_u32 v112, v112, s58, 8
	v_bfe_u32 v113, v113, s58, 8
	v_bfe_u32 v114, v114, s58, 8
	v_bfe_u32 v115, v115, s58, 8
	v_lshl_add_u32 v144, v112, 7, v58
	v_lshl_add_u32 v145, v113, 7, v58
	v_lshl_add_u32 v146, v114, 7, v58
	v_lshl_add_u32 v147, v115, 7, v58
	s_and_saveexec_b64 s[74:75], s[0:1]
	ds_add_u32 v144, v71
	s_mov_b64 exec, s[74:75]
	s_and_saveexec_b64 s[74:75], s[6:7]
	ds_add_u32 v145, v71
	s_mov_b64 exec, s[74:75]
	s_and_saveexec_b64 s[74:75], s[8:9]
	ds_add_u32 v146, v71
	s_mov_b64 exec, s[74:75]
	s_and_saveexec_b64 s[74:75], s[10:11]
	ds_add_u32 v147, v71
	s_mov_b64 exec, s[74:75]
.Lthr_g2_skip:
	v_ashrrev_i32_e32 v116, 31, v3
	v_ashrrev_i32_e32 v117, 31, v2
	v_ashrrev_i32_e32 v118, 31, v1
	v_ashrrev_i32_e32 v119, 31, v0
	v_bitop3_b32 v116, v116, v3, s67 bitop3:0x36
	v_bitop3_b32 v117, v117, v2, s67 bitop3:0x36
	v_bitop3_b32 v118, v118, v1, s67 bitop3:0x36
	v_bitop3_b32 v119, v119, v0, s67 bitop3:0x36
	v_lshrrev_b32_e32 v132, s62, v116
	v_lshrrev_b32_e32 v133, s62, v117
	v_lshrrev_b32_e32 v134, s62, v118
	v_lshrrev_b32_e32 v135, s62, v119
	v_cmp_eq_u32_e64 s[0:1], v132, v94
	v_cmp_eq_u32_e64 s[6:7], v133, v94
	v_cmp_eq_u32_e64 s[8:9], v134, v94
	v_cmp_eq_u32_e64 s[10:11], v135, v94
	s_or_b64 s[76:77], s[0:1], s[6:7]
	s_or_b64 s[84:85], s[8:9], s[10:11]
	s_or_b64 s[76:77], s[76:77], s[84:85]
	s_cbranch_scc0 .Lthr_g3_skip
	v_bfe_u32 v116, v116, s58, 8
	v_bfe_u32 v117, v117, s58, 8
	v_bfe_u32 v118, v118, s58, 8
	v_bfe_u32 v119, v119, s58, 8
	v_lshl_add_u32 v148, v116, 7, v58
	v_lshl_add_u32 v149, v117, 7, v58
	v_lshl_add_u32 v150, v118, 7, v58
	v_lshl_add_u32 v151, v119, 7, v58
	s_and_saveexec_b64 s[74:75], s[0:1]
	ds_add_u32 v148, v71
	s_mov_b64 exec, s[74:75]
	s_and_saveexec_b64 s[74:75], s[6:7]
	ds_add_u32 v149, v71
	s_mov_b64 exec, s[74:75]
	s_and_saveexec_b64 s[74:75], s[8:9]
	ds_add_u32 v150, v71
	s_mov_b64 exec, s[74:75]
	s_and_saveexec_b64 s[74:75], s[10:11]
	ds_add_u32 v151, v71
	s_mov_b64 exec, s[74:75]
.Lthr_g3_skip:
.Lthr_h_done:
	s_mov_b64 s[62:63], 0
	s_andn2_saveexec_b64 s[64:65], s[64:65]
	s_cbranch_execz .LBB0_270
